# v46 plus combine rows with loads up front, down-epilogue residual ring, norm-row gain preload (all three together)
# speedup vs baseline: 1.0065x; 1.0061x over previous
.LBB0_142:
	s_or_b64 exec, exec, s[4:5]
	v_readlane_b32 s65, v253, 2
	s_cmpk_gt_i32 s12, 0x3fff
	v_lshlrev_b32_e32 v26, 2, v22
	v_lshlrev_b32_e32 v30, 4, v22
	s_cbranch_scc1 .LBB0_147
	s_load_dwordx2 s[18:19], s[0:1], 0x0
	s_load_dwordx2 s[4:5], s[0:1], 0x28
	v_mov_b32_e32 v31, 0
	s_ashr_i32 s13, s12, 31
	v_mov_b32_e32 v27, v31
	v_lshl_add_u64 v[2:3], s[12:13], 3, v[26:27]
	s_mov_b64 s[6:7], 0x398a3000
	s_ashr_i32 s87, s86, 31
	s_lshl_b64 s[16:17], s[12:13], 12
	v_lshl_add_u64 v[40:41], v[2:3], 0, s[6:7]
	s_lshl_b64 s[6:7], s[86:87], 3
	v_lshl_or_b32 v42, v22, 3, s16
	v_mov_b32_e32 v43, s17
	s_lshl_b64 s[16:17], s[86:87], 12
	s_lshl_b64 s[22:23], s[12:13], 13
	s_waitcnt lgkmcnt(0)
	v_lshl_add_u64 v[28:29], s[4:5], 0, v[30:31]
	s_mov_b64 s[4:5], 0x1000
	s_add_u32 s18, s18, s22
	v_lshl_add_u64 v[32:33], v[28:29], 0, s[4:5]
	s_mov_b64 s[4:5], 0x1400
	s_addc_u32 s19, s19, s23
	v_lshl_add_u64 v[34:35], v[28:29], 0, s[4:5]
	s_mov_b64 s[4:5], 0x1800
	s_mov_b64 s[20:21], 0x1c00
	v_lshl_add_u64 v[2:3], s[18:19], 0, v[30:31]
	v_xor_b32_e32 v1, 4, v26
	v_xor_b32_e32 v23, 8, v26
	v_xor_b32_e32 v25, 16, v26
	v_xor_b32_e32 v48, 32, v26
	v_xor_b32_e32 v49, 64, v26
	v_xor_b32_e32 v50, 0x80, v26
	v_lshl_add_u64 v[36:37], v[28:29], 0, s[4:5]
	v_lshl_add_u64 v[38:39], v[28:29], 0, s[20:21]
	v_cmp_gt_u32_e64 s[4:5], 2, v22
	v_lshl_add_u64 v[44:45], v[2:3], 0, s[20:21]
	s_lshl_b64 s[18:19], s[86:87], 13
	v_mov_b32_e32 v27, 0x358637bd
	s_mov_b32 s13, 0x800000
	s_movk_i32 s22, 0x7fff
	s_mov_b32 s23, 0xaa43000
	v_mov_b32_e32 v51, 1
	s_mov_b32 s24, s12
	global_load_dwordx4 v[168:171], v[28:29], off
	global_load_dwordx4 v[172:175], v[28:29], off offset:1024
	global_load_dwordx4 v[176:179], v[28:29], off offset:2048
	global_load_dwordx4 v[180:183], v[28:29], off offset:3072
	global_load_dwordx4 v[184:187], v[32:33], off
	global_load_dwordx4 v[188:191], v[34:35], off
	global_load_dwordx4 v[192:195], v[36:37], off
	global_load_dwordx4 v[196:199], v[38:39], off
	s_waitcnt vmcnt(0)
	s_branch .LBB0_145

.LBB0_145:
	global_load_dwordx4 v[14:17], v[44:45], off offset:-3072
	global_load_dwordx4 v[10:13], v[44:45], off offset:-2048
	global_load_dwordx4 v[2:5], v[44:45], off
	global_load_dwordx4 v[6:9], v[44:45], off offset:-1024
	v_add_co_u32_e32 v46, vcc, 0xfffff000, v44
	s_nop 1
	v_addc_co_u32_e32 v47, vcc, -1, v45, vcc
	global_load_dwordx4 v[56:59], v[46:47], off offset:-3072
	global_load_dwordx4 v[60:63], v[46:47], off offset:-2048
	global_load_dwordx4 v[64:67], v[46:47], off offset:-1024
	global_load_dwordx4 v[18:21], v[44:45], off offset:-4096
	s_waitcnt vmcnt(4)
	v_mul_f32_e32 v91, v15, v15
	v_mov_b32_e32 v68, v168
	v_mov_b32_e32 v69, v169
	v_mov_b32_e32 v70, v170
	v_mov_b32_e32 v71, v171
	v_pk_mul_f32 v[46:47], v[12:13], v[12:13]
	v_pk_mul_f32 v[52:53], v[10:11], v[10:11]
	v_mul_f32_e32 v72, v7, v7
	v_mul_f32_e32 v74, v9, v9
	v_mul_f32_e32 v89, v4, v4
	v_mul_f32_e32 v96, v5, v5
	v_pk_mov_b32 v[76:77], v[52:53], v[46:47] op_sel:[1,0]
	v_mov_b32_e32 v53, v47
	v_pk_fma_f32 v[46:47], v[6:7], v[6:7], v[72:73] op_sel_hi:[1,1,0]
	v_pk_fma_f32 v[72:73], v[8:9], v[8:9], v[74:75] op_sel_hi:[1,1,0]
	v_pk_add_f32 v[52:53], v[76:77], v[52:53]
	v_mov_b32_e32 v47, v89
	v_mov_b32_e32 v73, v96
	v_pk_add_f32 v[46:47], v[46:47], v[72:73]
	v_mul_f32_e32 v55, v14, v14
	v_mul_f32_e32 v92, v16, v16
	v_mul_f32_e32 v93, v17, v17
	v_mul_f32_e32 v94, v2, v2
	v_mul_f32_e32 v95, v3, v3
	v_pk_add_f32 v[52:53], v[52:53], v[52:53] op_sel:[0,1] op_sel_hi:[1,0]
	s_waitcnt vmcnt(0)
	v_mov_b32_e32 v78, v57
	s_waitcnt vmcnt(3)
	v_mov_b32_e32 v79, v61
	v_mov_b32_e32 v82, v59
	v_mov_b32_e32 v83, v63
	v_mov_b32_e32 v74, v56
	v_mov_b32_e32 v75, v60
	v_mov_b32_e32 v80, v58
	v_mov_b32_e32 v81, v62
	s_waitcnt vmcnt(2)
	v_pk_mul_f32 v[84:85], v[66:67], v[66:67]
	v_pk_mul_f32 v[86:87], v[64:65], v[64:65]
	v_pk_mul_f32 v[76:77], v[78:79], v[78:79]
	v_pk_mul_f32 v[78:79], v[82:83], v[82:83]
	v_pk_mov_b32 v[82:83], v[86:87], v[84:85] op_sel:[1,0]
	v_mov_b32_e32 v87, v85
	v_pk_fma_f32 v[72:73], v[74:75], v[74:75], v[76:77]
	v_pk_fma_f32 v[74:75], v[80:81], v[80:81], v[78:79]
	s_waitcnt vmcnt(1)
	v_mul_f32_e32 v88, v19, v19
	v_mul_f32_e32 v90, v21, v21
	v_pk_add_f32 v[76:77], v[82:83], v[86:87]
	v_pk_add_f32 v[72:73], v[72:73], v[74:75]
	v_pk_fma_f32 v[84:85], v[18:19], v[18:19], v[88:89] op_sel_hi:[1,1,0]
	v_pk_fma_f32 v[88:89], v[20:21], v[20:21], v[90:91] op_sel_hi:[1,1,0]
	v_pk_add_f32 v[74:75], v[76:77], v[76:77] op_sel:[0,1] op_sel_hi:[1,0]
	v_pk_add_f32 v[72:73], v[72:73], v[72:73] op_sel:[0,1] op_sel_hi:[1,0]
	v_mov_b32_e32 v85, v92
	v_mov_b32_e32 v89, v93
	v_mov_b32_e32 v75, v91
	v_mov_b32_e32 v73, v55
	v_pk_add_f32 v[76:77], v[84:85], v[88:89]
	v_pk_add_f32 v[72:73], v[72:73], v[74:75]
	v_mov_b32_e32 v53, v95
	v_pk_add_f32 v[72:73], v[72:73], v[76:77]
	s_nop 0
	v_pk_add_f32 v[72:73], v[72:73], v[72:73] op_sel:[0,1] op_sel_hi:[1,0]
	s_nop 0
	v_mov_b32_e32 v73, v94
	v_pk_add_f32 v[52:53], v[72:73], v[52:53]
	s_nop 0
	v_pk_add_f32 v[46:47], v[52:53], v[46:47]
	s_nop 0
	v_add_f32_e32 v46, v46, v47
	ds_bpermute_b32 v47, v1, v46
	s_waitcnt lgkmcnt(0)
	v_add_f32_e32 v46, v46, v47
	ds_bpermute_b32 v47, v23, v46
	s_waitcnt lgkmcnt(0)
	v_add_f32_e32 v46, v46, v47
	ds_bpermute_b32 v47, v25, v46
	s_waitcnt lgkmcnt(0)
	v_add_f32_e32 v46, v46, v47
	ds_bpermute_b32 v47, v48, v46
	s_waitcnt lgkmcnt(0)
	v_add_f32_e32 v52, v46, v47
	ds_bpermute_b32 v53, v49, v52
	v_lshl_add_u64 v[46:47], s[14:15], 0, v[42:43]
	v_add_co_u32_e32 v46, vcc, s23, v46
	s_waitcnt lgkmcnt(0)
	v_add_f32_e32 v55, v52, v53
	ds_bpermute_b32 v72, v50, v55
	v_addc_co_u32_e32 v47, vcc, 0, v47, vcc
	s_waitcnt vmcnt(0)
	v_mov_b32_e32 v52, v68
	v_mov_b32_e32 v53, v70
	s_waitcnt lgkmcnt(0)
	v_add_f32_e32 v55, v55, v72
	v_fmamk_f32 v55, v55, 0x3a000000, v27
	v_mul_f32_e32 v68, 0x4b800000, v55
	v_cmp_gt_f32_e32 vcc, s13, v55
	v_mov_b32_e32 v70, v69
	v_mov_b32_e32 v69, v58
	v_cndmask_b32_e32 v55, v55, v68, vcc
	v_rsq_f32_e32 v55, v55
	v_mov_b32_e32 v68, v56
	v_mov_b32_e32 v58, v57
	v_mul_f32_e32 v56, 0x45800000, v55
	v_cndmask_b32_e32 v72, v55, v56, vcc
	v_pk_mul_f32 v[56:57], v[68:69], v[72:73] op_sel_hi:[1,0]
	v_pk_mul_f32 v[58:59], v[58:59], v[72:73] op_sel_hi:[1,0]
	v_pk_mul_f32 v[52:53], v[52:53], v[56:57]
	v_pk_mul_f32 v[56:57], v[70:71], v[58:59]
	v_and_b32_sdwa v55, v53, v51 dst_sel:DWORD dst_unused:UNUSED_PAD src0_sel:WORD_1 src1_sel:DWORD
	v_and_b32_sdwa v59, v57, v51 dst_sel:DWORD dst_unused:UNUSED_PAD src0_sel:WORD_1 src1_sel:DWORD
	v_and_b32_sdwa v68, v56, v51 dst_sel:DWORD dst_unused:UNUSED_PAD src0_sel:WORD_1 src1_sel:DWORD
	v_and_b32_sdwa v58, v52, v51 dst_sel:DWORD dst_unused:UNUSED_PAD src0_sel:WORD_1 src1_sel:DWORD
	v_add3_u32 v53, v53, v55, s22
	v_add3_u32 v55, v57, v59, s22
	v_add3_u32 v56, v56, v68, s22
	v_add3_u32 v52, v52, v58, s22
	v_and_b32_e32 v55, 0xffff0000, v55
	v_and_b32_e32 v56, 0xffff0000, v56
	v_or_b32_sdwa v53, v55, v53 dst_sel:DWORD dst_unused:UNUSED_PAD src0_sel:DWORD src1_sel:WORD_1
	v_or_b32_sdwa v52, v56, v52 dst_sel:DWORD dst_unused:UNUSED_PAD src0_sel:DWORD src1_sel:WORD_1
	flat_store_dwordx2 v[46:47], v[52:53]
	v_mov_b32_e32 v56, v172
	v_mov_b32_e32 v57, v173
	v_mov_b32_e32 v58, v174
	v_mov_b32_e32 v59, v175
	v_mov_b32_e32 v52, v60
	v_mov_b32_e32 v53, v62
	v_mov_b32_e32 v62, v61
	v_pk_mul_f32 v[52:53], v[52:53], v[72:73] op_sel_hi:[1,0]
	v_pk_mul_f32 v[60:61], v[62:63], v[72:73] op_sel_hi:[1,0]
	v_mov_b32_e32 v62, v56
	v_mov_b32_e32 v63, v58
	v_mov_b32_e32 v58, v57
	v_pk_mul_f32 v[52:53], v[62:63], v[52:53]
	v_pk_mul_f32 v[56:57], v[58:59], v[60:61]
	v_and_b32_sdwa v55, v53, v51 dst_sel:DWORD dst_unused:UNUSED_PAD src0_sel:WORD_1 src1_sel:DWORD
	v_and_b32_sdwa v59, v57, v51 dst_sel:DWORD dst_unused:UNUSED_PAD src0_sel:WORD_1 src1_sel:DWORD
	v_and_b32_sdwa v60, v56, v51 dst_sel:DWORD dst_unused:UNUSED_PAD src0_sel:WORD_1 src1_sel:DWORD
	v_and_b32_sdwa v58, v52, v51 dst_sel:DWORD dst_unused:UNUSED_PAD src0_sel:WORD_1 src1_sel:DWORD
	v_add3_u32 v53, v53, v55, s22
	v_add3_u32 v55, v57, v59, s22
	v_add3_u32 v56, v56, v60, s22
	v_add3_u32 v52, v52, v58, s22
	v_and_b32_e32 v55, 0xffff0000, v55
	v_and_b32_e32 v56, 0xffff0000, v56
	v_or_b32_sdwa v53, v55, v53 dst_sel:DWORD dst_unused:UNUSED_PAD src0_sel:DWORD src1_sel:WORD_1
	v_or_b32_sdwa v52, v56, v52 dst_sel:DWORD dst_unused:UNUSED_PAD src0_sel:DWORD src1_sel:WORD_1
	flat_store_dwordx2 v[46:47], v[52:53] offset:512
	v_mov_b32_e32 v56, v176
	v_mov_b32_e32 v57, v177
	v_mov_b32_e32 v58, v178
	v_mov_b32_e32 v59, v179
	v_mov_b32_e32 v52, v64
	v_mov_b32_e32 v53, v66
	v_mov_b32_e32 v66, v65
	v_pk_mul_f32 v[52:53], v[52:53], v[72:73] op_sel_hi:[1,0]
	v_pk_mul_f32 v[60:61], v[66:67], v[72:73] op_sel_hi:[1,0]
	v_mov_b32_e32 v62, v56
	v_mov_b32_e32 v63, v58
	v_mov_b32_e32 v58, v57
	v_pk_mul_f32 v[52:53], v[62:63], v[52:53]
	v_pk_mul_f32 v[56:57], v[58:59], v[60:61]
	v_and_b32_sdwa v55, v53, v51 dst_sel:DWORD dst_unused:UNUSED_PAD src0_sel:WORD_1 src1_sel:DWORD
	v_and_b32_sdwa v59, v57, v51 dst_sel:DWORD dst_unused:UNUSED_PAD src0_sel:WORD_1 src1_sel:DWORD
	v_and_b32_sdwa v60, v56, v51 dst_sel:DWORD dst_unused:UNUSED_PAD src0_sel:WORD_1 src1_sel:DWORD
	v_and_b32_sdwa v58, v52, v51 dst_sel:DWORD dst_unused:UNUSED_PAD src0_sel:WORD_1 src1_sel:DWORD
	v_add3_u32 v53, v53, v55, s22
	v_add3_u32 v55, v57, v59, s22
	v_add3_u32 v56, v56, v60, s22
	v_add3_u32 v52, v52, v58, s22
	v_and_b32_e32 v55, 0xffff0000, v55
	v_and_b32_e32 v56, 0xffff0000, v56
	v_or_b32_sdwa v53, v55, v53 dst_sel:DWORD dst_unused:UNUSED_PAD src0_sel:DWORD src1_sel:WORD_1
	v_or_b32_sdwa v52, v56, v52 dst_sel:DWORD dst_unused:UNUSED_PAD src0_sel:DWORD src1_sel:WORD_1
	flat_store_dwordx2 v[46:47], v[52:53] offset:1024
	v_mov_b32_e32 v56, v180
	v_mov_b32_e32 v57, v181
	v_mov_b32_e32 v58, v182
	v_mov_b32_e32 v59, v183
	v_mov_b32_e32 v52, v18
	v_mov_b32_e32 v53, v20
	v_mov_b32_e32 v20, v19
	v_pk_mul_f32 v[18:19], v[52:53], v[72:73] op_sel_hi:[1,0]
	v_pk_mul_f32 v[20:21], v[20:21], v[72:73] op_sel_hi:[1,0]
	v_mov_b32_e32 v53, v58
	v_mov_b32_e32 v58, v57
	v_mov_b32_e32 v52, v56
	v_pk_mul_f32 v[20:21], v[58:59], v[20:21]
	v_pk_mul_f32 v[18:19], v[52:53], v[18:19]
	v_and_b32_sdwa v55, v21, v51 dst_sel:DWORD dst_unused:UNUSED_PAD src0_sel:WORD_1 src1_sel:DWORD
	v_and_b32_sdwa v56, v20, v51 dst_sel:DWORD dst_unused:UNUSED_PAD src0_sel:WORD_1 src1_sel:DWORD
	v_and_b32_sdwa v52, v19, v51 dst_sel:DWORD dst_unused:UNUSED_PAD src0_sel:WORD_1 src1_sel:DWORD
	v_and_b32_sdwa v53, v18, v51 dst_sel:DWORD dst_unused:UNUSED_PAD src0_sel:WORD_1 src1_sel:DWORD
	v_add3_u32 v21, v21, v55, s22
	v_add3_u32 v20, v20, v56, s22
	v_add3_u32 v18, v18, v53, s22
	v_add3_u32 v19, v19, v52, s22
	v_and_b32_e32 v21, 0xffff0000, v21
	v_and_b32_e32 v20, 0xffff0000, v20
	v_or_b32_sdwa v19, v21, v19 dst_sel:DWORD dst_unused:UNUSED_PAD src0_sel:DWORD src1_sel:WORD_1
	v_or_b32_sdwa v18, v20, v18 dst_sel:DWORD dst_unused:UNUSED_PAD src0_sel:DWORD src1_sel:WORD_1
	flat_store_dwordx2 v[46:47], v[18:19] offset:1536
	v_mov_b32_e32 v18, v184
	v_mov_b32_e32 v19, v185
	v_mov_b32_e32 v20, v186
	v_mov_b32_e32 v21, v187
	v_mov_b32_e32 v52, v14
	v_mov_b32_e32 v53, v16
	v_mov_b32_e32 v16, v15
	v_pk_mul_f32 v[14:15], v[52:53], v[72:73] op_sel_hi:[1,0]
	v_pk_mul_f32 v[16:17], v[16:17], v[72:73] op_sel_hi:[1,0]
	v_mov_b32_e32 v53, v20
	v_mov_b32_e32 v20, v19
	v_mov_b32_e32 v52, v18
	v_pk_mul_f32 v[16:17], v[20:21], v[16:17]
	v_pk_mul_f32 v[14:15], v[52:53], v[14:15]
	v_and_b32_sdwa v20, v17, v51 dst_sel:DWORD dst_unused:UNUSED_PAD src0_sel:WORD_1 src1_sel:DWORD
	v_and_b32_sdwa v21, v16, v51 dst_sel:DWORD dst_unused:UNUSED_PAD src0_sel:WORD_1 src1_sel:DWORD
	v_and_b32_sdwa v18, v15, v51 dst_sel:DWORD dst_unused:UNUSED_PAD src0_sel:WORD_1 src1_sel:DWORD
	v_and_b32_sdwa v19, v14, v51 dst_sel:DWORD dst_unused:UNUSED_PAD src0_sel:WORD_1 src1_sel:DWORD
	v_add3_u32 v17, v17, v20, s22
	v_add3_u32 v16, v16, v21, s22
	v_add3_u32 v14, v14, v19, s22
	v_add3_u32 v15, v15, v18, s22
	v_and_b32_e32 v17, 0xffff0000, v17
	v_and_b32_e32 v16, 0xffff0000, v16
	v_or_b32_sdwa v15, v17, v15 dst_sel:DWORD dst_unused:UNUSED_PAD src0_sel:DWORD src1_sel:WORD_1
	v_or_b32_sdwa v14, v16, v14 dst_sel:DWORD dst_unused:UNUSED_PAD src0_sel:DWORD src1_sel:WORD_1
	flat_store_dwordx2 v[46:47], v[14:15] offset:2048
	v_mov_b32_e32 v14, v188
	v_mov_b32_e32 v15, v189
	v_mov_b32_e32 v16, v190
	v_mov_b32_e32 v17, v191
	v_mov_b32_e32 v18, v10
	v_mov_b32_e32 v19, v12
	v_mov_b32_e32 v12, v11
	v_pk_mul_f32 v[10:11], v[18:19], v[72:73] op_sel_hi:[1,0]
	v_pk_mul_f32 v[12:13], v[12:13], v[72:73] op_sel_hi:[1,0]
	v_mov_b32_e32 v19, v16
	v_mov_b32_e32 v16, v15
	v_mov_b32_e32 v18, v14
	v_pk_mul_f32 v[12:13], v[16:17], v[12:13]
	v_pk_mul_f32 v[10:11], v[18:19], v[10:11]
	v_and_b32_sdwa v16, v13, v51 dst_sel:DWORD dst_unused:UNUSED_PAD src0_sel:WORD_1 src1_sel:DWORD
	v_and_b32_sdwa v17, v12, v51 dst_sel:DWORD dst_unused:UNUSED_PAD src0_sel:WORD_1 src1_sel:DWORD
	v_and_b32_sdwa v14, v11, v51 dst_sel:DWORD dst_unused:UNUSED_PAD src0_sel:WORD_1 src1_sel:DWORD
	v_and_b32_sdwa v15, v10, v51 dst_sel:DWORD dst_unused:UNUSED_PAD src0_sel:WORD_1 src1_sel:DWORD
	v_add3_u32 v13, v13, v16, s22
	v_add3_u32 v12, v12, v17, s22
	v_add3_u32 v10, v10, v15, s22
	v_add3_u32 v11, v11, v14, s22
	v_and_b32_e32 v13, 0xffff0000, v13
	v_and_b32_e32 v12, 0xffff0000, v12
	v_or_b32_sdwa v11, v13, v11 dst_sel:DWORD dst_unused:UNUSED_PAD src0_sel:DWORD src1_sel:WORD_1
	v_or_b32_sdwa v10, v12, v10 dst_sel:DWORD dst_unused:UNUSED_PAD src0_sel:DWORD src1_sel:WORD_1
	flat_store_dwordx2 v[46:47], v[10:11] offset:2560
	v_mov_b32_e32 v10, v192
	v_mov_b32_e32 v11, v193
	v_mov_b32_e32 v12, v194
	v_mov_b32_e32 v13, v195
	v_mov_b32_e32 v14, v6
	v_mov_b32_e32 v15, v8
	v_mov_b32_e32 v8, v7
	v_pk_mul_f32 v[6:7], v[14:15], v[72:73] op_sel_hi:[1,0]
	v_pk_mul_f32 v[8:9], v[8:9], v[72:73] op_sel_hi:[1,0]
	v_mov_b32_e32 v15, v12
	v_mov_b32_e32 v12, v11
	v_mov_b32_e32 v14, v10
	v_pk_mul_f32 v[8:9], v[8:9], v[12:13]
	v_pk_mul_f32 v[6:7], v[6:7], v[14:15]
	v_and_b32_sdwa v12, v9, v51 dst_sel:DWORD dst_unused:UNUSED_PAD src0_sel:WORD_1 src1_sel:DWORD
	v_and_b32_sdwa v13, v8, v51 dst_sel:DWORD dst_unused:UNUSED_PAD src0_sel:WORD_1 src1_sel:DWORD
	v_and_b32_sdwa v10, v7, v51 dst_sel:DWORD dst_unused:UNUSED_PAD src0_sel:WORD_1 src1_sel:DWORD
	v_and_b32_sdwa v11, v6, v51 dst_sel:DWORD dst_unused:UNUSED_PAD src0_sel:WORD_1 src1_sel:DWORD
	v_add3_u32 v9, v9, v12, s22
	v_add3_u32 v8, v8, v13, s22
	v_add3_u32 v6, v6, v11, s22
	v_add3_u32 v7, v7, v10, s22
	v_and_b32_e32 v9, 0xffff0000, v9
	v_and_b32_e32 v8, 0xffff0000, v8
	v_or_b32_sdwa v7, v9, v7 dst_sel:DWORD dst_unused:UNUSED_PAD src0_sel:DWORD src1_sel:WORD_1
	v_or_b32_sdwa v6, v8, v6 dst_sel:DWORD dst_unused:UNUSED_PAD src0_sel:DWORD src1_sel:WORD_1
	flat_store_dwordx2 v[46:47], v[6:7] offset:3072
	v_mov_b32_e32 v6, v196
	v_mov_b32_e32 v7, v197
	v_mov_b32_e32 v8, v198
	v_mov_b32_e32 v9, v199
	v_mov_b32_e32 v10, v2
	v_mov_b32_e32 v11, v4
	v_mov_b32_e32 v4, v3
	v_pk_mul_f32 v[2:3], v[10:11], v[72:73] op_sel_hi:[1,0]
	v_pk_mul_f32 v[4:5], v[4:5], v[72:73] op_sel_hi:[1,0]
	v_mov_b32_e32 v11, v8
	v_mov_b32_e32 v8, v7
	v_mov_b32_e32 v10, v6
	v_pk_mul_f32 v[4:5], v[4:5], v[8:9]
	v_pk_mul_f32 v[2:3], v[2:3], v[10:11]
	v_and_b32_sdwa v8, v5, v51 dst_sel:DWORD dst_unused:UNUSED_PAD src0_sel:WORD_1 src1_sel:DWORD
	v_and_b32_sdwa v9, v4, v51 dst_sel:DWORD dst_unused:UNUSED_PAD src0_sel:WORD_1 src1_sel:DWORD
	v_and_b32_sdwa v6, v3, v51 dst_sel:DWORD dst_unused:UNUSED_PAD src0_sel:WORD_1 src1_sel:DWORD
	v_and_b32_sdwa v7, v2, v51 dst_sel:DWORD dst_unused:UNUSED_PAD src0_sel:WORD_1 src1_sel:DWORD
	v_add3_u32 v5, v5, v8, s22
	v_add3_u32 v4, v4, v9, s22
	v_add3_u32 v2, v2, v7, s22
	v_add3_u32 v3, v3, v6, s22
	v_and_b32_e32 v5, 0xffff0000, v5
	v_and_b32_e32 v4, 0xffff0000, v4
	v_or_b32_sdwa v3, v5, v3 dst_sel:DWORD dst_unused:UNUSED_PAD src0_sel:DWORD src1_sel:WORD_1
	v_or_b32_sdwa v2, v4, v2 dst_sel:DWORD dst_unused:UNUSED_PAD src0_sel:DWORD src1_sel:WORD_1
	flat_store_dwordx2 v[46:47], v[2:3] offset:3584
	s_and_saveexec_b64 s[20:21], s[4:5]
	s_cbranch_execz .LBB0_144
	v_lshl_add_u64 v[2:3], s[14:15], 0, v[40:41]
	flat_store_dword v[2:3], v31
	s_branch .LBB0_144

.LBB0_189:
	s_andn2_b64 vcc, exec, s[0:1]
	s_mov_b32 s94, s83
	s_cbranch_vccnz .LBB0_305
	s_cmp_lt_u32 s83, 4
	s_cselect_b64 s[22:23], -1, 0
	s_cmp_gt_u32 s83, 3
	s_cbranch_scc1 .LBB0_194
	v_mbcnt_lo_u32_b32 v0, -1, 0
	v_mbcnt_hi_u32_b32 v0, -1, v0
	v_readlane_b32 s1, v253, 3
	v_add_u32_e32 v1, s65, v0
	v_readlane_b32 s12, v253, 0
	v_readfirstlane_b32 s0, v1
	s_ashr_i32 s0, s0, 6
	s_add_i32 s0, s0, s1
	v_readlane_b32 s13, v253, 1
	s_cmpk_gt_i32 s0, 0x1fff
	s_cbranch_scc1 .LBB0_194
	v_and_b32_e32 v0, 63, v0
	v_readlane_b32 s18, v255, 26
	v_lshlrev_b32_e32 v96, 4, v0
	v_readlane_b32 s19, v255, 27
	s_xor_b32 s14, s26, 0x3000000
	s_mov_b32 s15, s27
	v_lshl_add_u64 v[32:33], s[18:19], 0, v[96:97]
	s_mov_b64 s[18:19], 0x1000
	v_lshl_add_u64 v[34:35], v[32:33], 0, s[18:19]
	s_mov_b64 s[18:19], 0x1400
	v_lshl_add_u64 v[36:37], v[32:33], 0, s[18:19]
	s_mov_b64 s[18:19], 0x1800
	v_lshl_add_u64 v[38:39], v[32:33], 0, s[18:19]
	s_mov_b64 s[18:19], 0x1c00
	s_ashr_i32 s1, s0, 31
	v_lshl_add_u64 v[40:41], v[32:33], 0, s[18:19]
	s_lshl_b64 s[18:19], s[0:1], 12
	s_lshl_b64 s[14:15], s[14:15], 1
	s_add_u32 s12, s12, s14
	s_addc_u32 s13, s13, s15
	v_lshlrev_b32_e32 v1, 2, v0
	s_add_u32 s12, s12, s18
	v_xor_b32_e32 v47, 4, v1
	v_xor_b32_e32 v50, 8, v1
	v_xor_b32_e32 v51, 16, v1
	v_xor_b32_e32 v52, 32, v1
	v_xor_b32_e32 v53, 64, v1
	v_xor_b32_e32 v54, 0x80, v1
	v_lshlrev_b32_e32 v0, 3, v0
	v_mov_b32_e32 v1, v97
	s_addc_u32 s13, s13, s19
	v_readlane_b32 s14, v255, 52
	v_lshl_add_u64 v[0:1], s[12:13], 0, v[0:1]
	s_mov_b64 s[12:13], 0xaa43000
	v_readlane_b32 s15, v255, 53
	v_lshl_add_u64 v[42:43], v[0:1], 0, s[12:13]
	s_lshl_b64 s[12:13], s[0:1], 13
	s_lshl_b64 s[14:15], s[14:15], 2
	v_readlane_b32 s1, v255, 11
	s_add_u32 s1, s1, s14
	v_readlane_b32 s14, v255, 12
	s_addc_u32 s14, s14, s15
	s_add_u32 s12, s1, s12
	s_addc_u32 s13, s14, s13
	v_lshl_add_u64 v[44:45], s[12:13], 0, v[96:97]
	global_load_dwordx4 v[64:67], v[32:33], off
	global_load_dwordx4 v[68:71], v[32:33], off offset:1024
	global_load_dwordx4 v[72:75], v[32:33], off offset:2048
	global_load_dwordx4 v[76:79], v[32:33], off offset:3072
	global_load_dwordx4 v[80:83], v[34:35], off
	global_load_dwordx4 v[84:87], v[36:37], off
	global_load_dwordx4 v[88:91], v[38:39], off
	global_load_dwordx4 v[92:95], v[40:41], off
	s_waitcnt vmcnt(0)
.LBB0_193:
	v_add_co_u32_e32 v0, vcc, 0xfffff000, v44
	s_add_i32 s0, s0, s86
	s_nop 0
	v_addc_co_u32_e32 v1, vcc, -1, v45, vcc
	global_load_dwordx4 v[28:31], v[0:1], off offset:-3072
	global_load_dwordx4 v[24:27], v[0:1], off offset:-2048
	global_load_dwordx4 v[20:23], v[0:1], off offset:-1024
	global_load_dwordx4 v[8:11], v[44:45], off offset:-4096
	global_load_dwordx4 v[12:15], v[44:45], off offset:-3072
	global_load_dwordx4 v[16:19], v[44:45], off offset:-2048
	s_cmpk_lt_i32 s0, 0x2000
	s_waitcnt vmcnt(0)
	v_mov_b32_e32 v4, v29
	v_mov_b32_e32 v5, v25
	v_mov_b32_e32 v2, v28
	v_mov_b32_e32 v3, v24
	v_pk_mul_f32 v[4:5], v[4:5], v[4:5]
	v_mov_b32_e32 v6, v31
	v_mov_b32_e32 v7, v27
	v_pk_fma_f32 v[2:3], v[2:3], v[2:3], v[4:5]
	v_mov_b32_e32 v4, v30
	v_mov_b32_e32 v5, v26
	v_pk_mul_f32 v[6:7], v[6:7], v[6:7]
	v_pk_mul_f32 v[0:1], v[22:23], v[22:23]
	v_pk_fma_f32 v[4:5], v[4:5], v[4:5], v[6:7]
	s_nop 0
	v_pk_add_f32 v[2:3], v[2:3], v[4:5]
	v_pk_mul_f32 v[4:5], v[20:21], v[20:21]
	v_pk_add_f32 v[2:3], v[2:3], v[2:3] op_sel:[0,1] op_sel_hi:[1,0]
	v_pk_mov_b32 v[6:7], v[4:5], v[0:1] op_sel:[1,0]
	v_mov_b32_e32 v5, v1
	v_pk_add_f32 v[0:1], v[6:7], v[4:5]
	v_mul_f32_e32 v4, v12, v12
	v_mul_f32_e32 v5, v13, v13
	v_pk_add_f32 v[0:1], v[0:1], v[0:1] op_sel:[0,1] op_sel_hi:[1,0]
	v_mov_b32_e32 v3, v4
	v_mov_b32_e32 v1, v5
	v_pk_add_f32 v[0:1], v[2:3], v[0:1]
	v_mul_f32_e32 v2, v9, v9
	v_mul_f32_e32 v4, v11, v11
	v_mul_f32_e32 v6, v14, v14
	v_mul_f32_e32 v7, v15, v15
	v_pk_fma_f32 v[2:3], v[8:9], v[8:9], v[2:3] op_sel_hi:[1,1,0]
	v_pk_fma_f32 v[4:5], v[10:11], v[10:11], v[4:5] op_sel_hi:[1,1,0]
	v_mov_b32_e32 v3, v6
	v_mov_b32_e32 v5, v7
	v_pk_add_f32 v[2:3], v[2:3], v[4:5]
	s_nop 0
	v_pk_add_f32 v[48:49], v[0:1], v[2:3]
	v_pk_mul_f32 v[0:1], v[18:19], v[18:19]
	v_pk_mul_f32 v[2:3], v[16:17], v[16:17]
	v_pk_add_f32 v[48:49], v[48:49], v[48:49] op_sel:[0,1] op_sel_hi:[1,0]
	v_pk_mov_b32 v[4:5], v[2:3], v[0:1] op_sel:[1,0]
	v_mov_b32_e32 v3, v1
	v_pk_add_f32 v[56:57], v[4:5], v[2:3]
	global_load_dwordx4 v[4:7], v[44:45], off offset:-1024
	global_load_dwordx4 v[0:3], v[44:45], off
	v_pk_add_f32 v[56:57], v[56:57], v[56:57] op_sel:[0,1] op_sel_hi:[1,0]
	v_lshl_add_u64 v[44:45], v[44:45], 0, s[84:85]
	s_waitcnt vmcnt(0)
	v_mul_f32_e32 v46, v0, v0
	v_mul_f32_e32 v55, v1, v1
	v_mov_b32_e32 v49, v46
	v_mov_b32_e32 v57, v55
	v_mul_f32_e32 v46, v5, v5
	v_mul_f32_e32 v58, v2, v2
	v_pk_add_f32 v[48:49], v[48:49], v[56:57]
	v_pk_fma_f32 v[56:57], v[4:5], v[4:5], v[46:47] op_sel_hi:[1,1,0]
	v_mul_f32_e32 v46, v7, v7
	v_mul_f32_e32 v60, v3, v3
	v_mov_b32_e32 v57, v58
	v_pk_fma_f32 v[58:59], v[6:7], v[6:7], v[46:47] op_sel_hi:[1,1,0]
	s_nop 0
	v_mov_b32_e32 v59, v60
	v_pk_add_f32 v[56:57], v[56:57], v[58:59]
	s_nop 0
	v_pk_add_f32 v[48:49], v[48:49], v[56:57]
	v_mov_b32_e32 v56, v64
	v_mov_b32_e32 v57, v65
	v_mov_b32_e32 v58, v66
	v_mov_b32_e32 v59, v67
	v_add_f32_e32 v46, v48, v49
	ds_bpermute_b32 v48, v47, v46
	v_mov_b32_e32 v49, v30
	v_mov_b32_e32 v30, v29
	s_waitcnt lgkmcnt(0)
	v_add_f32_e32 v46, v46, v48
	ds_bpermute_b32 v48, v50, v46
	s_waitcnt lgkmcnt(0)
	v_add_f32_e32 v46, v46, v48
	ds_bpermute_b32 v48, v51, v46
	s_waitcnt lgkmcnt(0)
	v_add_f32_e32 v46, v46, v48
	ds_bpermute_b32 v48, v52, v46
	s_waitcnt lgkmcnt(0)
	v_add_f32_e32 v46, v46, v48
	ds_bpermute_b32 v48, v53, v46
	s_waitcnt lgkmcnt(0)
	v_add_f32_e32 v46, v46, v48
	ds_bpermute_b32 v48, v54, v46
	s_waitcnt lgkmcnt(0)
	v_add_f32_e32 v46, v46, v48
	v_fmamk_f32 v46, v46, 0x3a000000, v194
	v_cmp_gt_f32_e32 vcc, s38, v46
	v_mul_f32_e32 v48, 0x4b800000, v46
	s_waitcnt vmcnt(0)
	v_mov_b32_e32 v60, v56
	v_cndmask_b32_e32 v46, v46, v48, vcc
	v_rsq_f32_e32 v46, v46
	v_mov_b32_e32 v61, v58
	v_mov_b32_e32 v58, v57
	v_mul_f32_e32 v48, 0x45800000, v46
	v_cndmask_b32_e32 v46, v46, v48, vcc
	v_mov_b32_e32 v48, v28
	v_pk_mul_f32 v[48:49], v[48:49], v[46:47] op_sel_hi:[1,0]
	v_pk_mul_f32 v[28:29], v[30:31], v[46:47] op_sel_hi:[1,0]
	v_pk_mul_f32 v[48:49], v[60:61], v[48:49]
	v_pk_mul_f32 v[28:29], v[58:59], v[28:29]
	v_and_b32_sdwa v30, v49, v195 dst_sel:DWORD dst_unused:UNUSED_PAD src0_sel:WORD_1 src1_sel:DWORD
	v_and_b32_sdwa v31, v48, v195 dst_sel:DWORD dst_unused:UNUSED_PAD src0_sel:WORD_1 src1_sel:DWORD
	v_add3_u32 v31, v48, v31, s39
	v_add3_u32 v30, v49, v30, s39
	v_and_b32_sdwa v48, v29, v195 dst_sel:DWORD dst_unused:UNUSED_PAD src0_sel:WORD_1 src1_sel:DWORD
	v_and_b32_sdwa v49, v28, v195 dst_sel:DWORD dst_unused:UNUSED_PAD src0_sel:WORD_1 src1_sel:DWORD
	v_add3_u32 v29, v29, v48, s39
	v_add3_u32 v28, v28, v49, s39
	v_and_b32_e32 v29, 0xffff0000, v29
	v_and_b32_e32 v28, 0xffff0000, v28
	v_or_b32_sdwa v29, v29, v30 dst_sel:DWORD dst_unused:UNUSED_PAD src0_sel:DWORD src1_sel:WORD_1
	v_or_b32_sdwa v28, v28, v31 dst_sel:DWORD dst_unused:UNUSED_PAD src0_sel:DWORD src1_sel:WORD_1
	flat_store_dwordx2 v[42:43], v[28:29]
	v_mov_b32_e32 v28, v68
	v_mov_b32_e32 v29, v69
	v_mov_b32_e32 v30, v70
	v_mov_b32_e32 v31, v71
	v_mov_b32_e32 v49, v26
	v_mov_b32_e32 v26, v25
	v_mov_b32_e32 v48, v24
	v_pk_mul_f32 v[24:25], v[26:27], v[46:47] op_sel_hi:[1,0]
	v_pk_mul_f32 v[48:49], v[48:49], v[46:47] op_sel_hi:[1,0]
	v_mov_b32_e32 v57, v30
	v_mov_b32_e32 v30, v29
	v_mov_b32_e32 v56, v28
	v_pk_mul_f32 v[24:25], v[30:31], v[24:25]
	v_pk_mul_f32 v[48:49], v[56:57], v[48:49]
	v_and_b32_sdwa v28, v25, v195 dst_sel:DWORD dst_unused:UNUSED_PAD src0_sel:WORD_1 src1_sel:DWORD
	v_and_b32_sdwa v29, v24, v195 dst_sel:DWORD dst_unused:UNUSED_PAD src0_sel:WORD_1 src1_sel:DWORD
	v_and_b32_sdwa v26, v49, v195 dst_sel:DWORD dst_unused:UNUSED_PAD src0_sel:WORD_1 src1_sel:DWORD
	v_and_b32_sdwa v27, v48, v195 dst_sel:DWORD dst_unused:UNUSED_PAD src0_sel:WORD_1 src1_sel:DWORD
	v_add3_u32 v25, v25, v28, s39
	v_add3_u32 v24, v24, v29, s39
	v_add3_u32 v27, v48, v27, s39
	v_add3_u32 v26, v49, v26, s39
	v_and_b32_e32 v25, 0xffff0000, v25
	v_and_b32_e32 v24, 0xffff0000, v24
	v_or_b32_sdwa v25, v25, v26 dst_sel:DWORD dst_unused:UNUSED_PAD src0_sel:DWORD src1_sel:WORD_1
	v_or_b32_sdwa v24, v24, v27 dst_sel:DWORD dst_unused:UNUSED_PAD src0_sel:DWORD src1_sel:WORD_1
	flat_store_dwordx2 v[42:43], v[24:25] offset:512
	v_mov_b32_e32 v24, v72
	v_mov_b32_e32 v25, v73
	v_mov_b32_e32 v26, v74
	v_mov_b32_e32 v27, v75
	v_mov_b32_e32 v29, v22
	v_mov_b32_e32 v22, v21
	v_mov_b32_e32 v28, v20
	v_pk_mul_f32 v[20:21], v[22:23], v[46:47] op_sel_hi:[1,0]
	v_pk_mul_f32 v[28:29], v[28:29], v[46:47] op_sel_hi:[1,0]
	v_mov_b32_e32 v31, v26
	v_mov_b32_e32 v26, v25
	v_mov_b32_e32 v30, v24
	v_pk_mul_f32 v[20:21], v[26:27], v[20:21]
	v_pk_mul_f32 v[28:29], v[30:31], v[28:29]
	v_and_b32_sdwa v24, v21, v195 dst_sel:DWORD dst_unused:UNUSED_PAD src0_sel:WORD_1 src1_sel:DWORD
	v_and_b32_sdwa v25, v20, v195 dst_sel:DWORD dst_unused:UNUSED_PAD src0_sel:WORD_1 src1_sel:DWORD
	v_and_b32_sdwa v22, v29, v195 dst_sel:DWORD dst_unused:UNUSED_PAD src0_sel:WORD_1 src1_sel:DWORD
	v_and_b32_sdwa v23, v28, v195 dst_sel:DWORD dst_unused:UNUSED_PAD src0_sel:WORD_1 src1_sel:DWORD
	v_add3_u32 v21, v21, v24, s39
	v_add3_u32 v20, v20, v25, s39
	v_add3_u32 v23, v28, v23, s39
	v_add3_u32 v22, v29, v22, s39
	v_and_b32_e32 v21, 0xffff0000, v21
	v_and_b32_e32 v20, 0xffff0000, v20
	v_or_b32_sdwa v21, v21, v22 dst_sel:DWORD dst_unused:UNUSED_PAD src0_sel:DWORD src1_sel:WORD_1
	v_or_b32_sdwa v20, v20, v23 dst_sel:DWORD dst_unused:UNUSED_PAD src0_sel:DWORD src1_sel:WORD_1
	flat_store_dwordx2 v[42:43], v[20:21] offset:1024
	v_mov_b32_e32 v20, v76
	v_mov_b32_e32 v21, v77
	v_mov_b32_e32 v22, v78
	v_mov_b32_e32 v23, v79
	v_mov_b32_e32 v25, v10
	v_mov_b32_e32 v10, v9
	v_mov_b32_e32 v24, v8
	v_pk_mul_f32 v[8:9], v[10:11], v[46:47] op_sel_hi:[1,0]
	v_pk_mul_f32 v[24:25], v[24:25], v[46:47] op_sel_hi:[1,0]
	v_mov_b32_e32 v27, v22
	v_mov_b32_e32 v22, v21
	v_mov_b32_e32 v26, v20
	v_pk_mul_f32 v[8:9], v[22:23], v[8:9]
	v_pk_mul_f32 v[24:25], v[26:27], v[24:25]
	v_and_b32_sdwa v20, v9, v195 dst_sel:DWORD dst_unused:UNUSED_PAD src0_sel:WORD_1 src1_sel:DWORD
	v_and_b32_sdwa v21, v8, v195 dst_sel:DWORD dst_unused:UNUSED_PAD src0_sel:WORD_1 src1_sel:DWORD
	v_and_b32_sdwa v10, v25, v195 dst_sel:DWORD dst_unused:UNUSED_PAD src0_sel:WORD_1 src1_sel:DWORD
	v_and_b32_sdwa v11, v24, v195 dst_sel:DWORD dst_unused:UNUSED_PAD src0_sel:WORD_1 src1_sel:DWORD
	v_add3_u32 v9, v9, v20, s39
	v_add3_u32 v8, v8, v21, s39
	v_add3_u32 v11, v24, v11, s39
	v_add3_u32 v10, v25, v10, s39
	v_and_b32_e32 v9, 0xffff0000, v9
	v_and_b32_e32 v8, 0xffff0000, v8
	v_or_b32_sdwa v9, v9, v10 dst_sel:DWORD dst_unused:UNUSED_PAD src0_sel:DWORD src1_sel:WORD_1
	v_or_b32_sdwa v8, v8, v11 dst_sel:DWORD dst_unused:UNUSED_PAD src0_sel:DWORD src1_sel:WORD_1
	flat_store_dwordx2 v[42:43], v[8:9] offset:1536
	v_mov_b32_e32 v8, v80
	v_mov_b32_e32 v9, v81
	v_mov_b32_e32 v10, v82
	v_mov_b32_e32 v11, v83
	v_mov_b32_e32 v21, v14
	v_mov_b32_e32 v14, v13
	v_mov_b32_e32 v20, v12
	v_pk_mul_f32 v[12:13], v[14:15], v[46:47] op_sel_hi:[1,0]
	v_pk_mul_f32 v[20:21], v[20:21], v[46:47] op_sel_hi:[1,0]
	v_mov_b32_e32 v23, v10
	v_mov_b32_e32 v10, v9
	v_mov_b32_e32 v22, v8
	v_pk_mul_f32 v[8:9], v[10:11], v[12:13]
	v_pk_mul_f32 v[20:21], v[22:23], v[20:21]
	v_and_b32_sdwa v12, v9, v195 dst_sel:DWORD dst_unused:UNUSED_PAD src0_sel:WORD_1 src1_sel:DWORD
	v_and_b32_sdwa v13, v8, v195 dst_sel:DWORD dst_unused:UNUSED_PAD src0_sel:WORD_1 src1_sel:DWORD
	v_and_b32_sdwa v10, v21, v195 dst_sel:DWORD dst_unused:UNUSED_PAD src0_sel:WORD_1 src1_sel:DWORD
	v_and_b32_sdwa v11, v20, v195 dst_sel:DWORD dst_unused:UNUSED_PAD src0_sel:WORD_1 src1_sel:DWORD
	v_add3_u32 v9, v9, v12, s39
	v_add3_u32 v8, v8, v13, s39
	v_add3_u32 v11, v20, v11, s39
	v_add3_u32 v10, v21, v10, s39
	v_and_b32_e32 v9, 0xffff0000, v9
	v_and_b32_e32 v8, 0xffff0000, v8
	v_or_b32_sdwa v9, v9, v10 dst_sel:DWORD dst_unused:UNUSED_PAD src0_sel:DWORD src1_sel:WORD_1
	v_or_b32_sdwa v8, v8, v11 dst_sel:DWORD dst_unused:UNUSED_PAD src0_sel:DWORD src1_sel:WORD_1
	flat_store_dwordx2 v[42:43], v[8:9] offset:2048
	v_mov_b32_e32 v8, v84
	v_mov_b32_e32 v9, v85
	v_mov_b32_e32 v10, v86
	v_mov_b32_e32 v11, v87
	v_mov_b32_e32 v12, v16
	v_mov_b32_e32 v13, v18
	v_pk_mul_f32 v[12:13], v[12:13], v[46:47] op_sel_hi:[1,0]
	v_mov_b32_e32 v18, v17
	v_mov_b32_e32 v14, v8
	v_mov_b32_e32 v15, v10
	v_pk_mul_f32 v[12:13], v[14:15], v[12:13]
	v_pk_mul_f32 v[14:15], v[18:19], v[46:47] op_sel_hi:[1,0]
	v_mov_b32_e32 v10, v9
	v_pk_mul_f32 v[8:9], v[10:11], v[14:15]
	v_and_b32_sdwa v10, v13, v195 dst_sel:DWORD dst_unused:UNUSED_PAD src0_sel:WORD_1 src1_sel:DWORD
	v_and_b32_sdwa v11, v12, v195 dst_sel:DWORD dst_unused:UNUSED_PAD src0_sel:WORD_1 src1_sel:DWORD
	v_add3_u32 v11, v12, v11, s39
	v_add3_u32 v10, v13, v10, s39
	v_and_b32_sdwa v12, v9, v195 dst_sel:DWORD dst_unused:UNUSED_PAD src0_sel:WORD_1 src1_sel:DWORD
	v_and_b32_sdwa v13, v8, v195 dst_sel:DWORD dst_unused:UNUSED_PAD src0_sel:WORD_1 src1_sel:DWORD
	v_add3_u32 v9, v9, v12, s39
	v_add3_u32 v8, v8, v13, s39
	v_and_b32_e32 v9, 0xffff0000, v9
	v_and_b32_e32 v8, 0xffff0000, v8
	v_or_b32_sdwa v9, v9, v10 dst_sel:DWORD dst_unused:UNUSED_PAD src0_sel:DWORD src1_sel:WORD_1
	v_or_b32_sdwa v8, v8, v11 dst_sel:DWORD dst_unused:UNUSED_PAD src0_sel:DWORD src1_sel:WORD_1
	flat_store_dwordx2 v[42:43], v[8:9] offset:2560
	v_mov_b32_e32 v8, v88
	v_mov_b32_e32 v9, v89
	v_mov_b32_e32 v10, v90
	v_mov_b32_e32 v11, v91
	v_mov_b32_e32 v13, v6
	v_mov_b32_e32 v6, v5
	v_mov_b32_e32 v12, v4
	v_pk_mul_f32 v[4:5], v[6:7], v[46:47] op_sel_hi:[1,0]
	v_pk_mul_f32 v[12:13], v[12:13], v[46:47] op_sel_hi:[1,0]
	v_mov_b32_e32 v15, v10
	v_mov_b32_e32 v10, v9
	v_mov_b32_e32 v14, v8
	v_pk_mul_f32 v[4:5], v[4:5], v[10:11]
	v_pk_mul_f32 v[12:13], v[12:13], v[14:15]
	v_and_b32_sdwa v8, v5, v195 dst_sel:DWORD dst_unused:UNUSED_PAD src0_sel:WORD_1 src1_sel:DWORD
	v_and_b32_sdwa v9, v4, v195 dst_sel:DWORD dst_unused:UNUSED_PAD src0_sel:WORD_1 src1_sel:DWORD
	v_and_b32_sdwa v6, v13, v195 dst_sel:DWORD dst_unused:UNUSED_PAD src0_sel:WORD_1 src1_sel:DWORD
	v_and_b32_sdwa v7, v12, v195 dst_sel:DWORD dst_unused:UNUSED_PAD src0_sel:WORD_1 src1_sel:DWORD
	v_add3_u32 v5, v5, v8, s39
	v_add3_u32 v4, v4, v9, s39
	v_add3_u32 v7, v12, v7, s39
	v_add3_u32 v6, v13, v6, s39
	v_and_b32_e32 v5, 0xffff0000, v5
	v_and_b32_e32 v4, 0xffff0000, v4
	v_or_b32_sdwa v5, v5, v6 dst_sel:DWORD dst_unused:UNUSED_PAD src0_sel:DWORD src1_sel:WORD_1
	v_or_b32_sdwa v4, v4, v7 dst_sel:DWORD dst_unused:UNUSED_PAD src0_sel:DWORD src1_sel:WORD_1
	flat_store_dwordx2 v[42:43], v[4:5] offset:3072
	v_mov_b32_e32 v4, v92
	v_mov_b32_e32 v5, v93
	v_mov_b32_e32 v6, v94
	v_mov_b32_e32 v7, v95
	v_mov_b32_e32 v9, v2
	v_mov_b32_e32 v2, v1
	v_mov_b32_e32 v8, v0
	v_pk_mul_f32 v[0:1], v[2:3], v[46:47] op_sel_hi:[1,0]
	v_pk_mul_f32 v[8:9], v[8:9], v[46:47] op_sel_hi:[1,0]
	v_mov_b32_e32 v11, v6
	v_mov_b32_e32 v6, v5
	v_mov_b32_e32 v10, v4
	v_pk_mul_f32 v[0:1], v[0:1], v[6:7]
	v_pk_mul_f32 v[8:9], v[8:9], v[10:11]
	v_and_b32_sdwa v4, v1, v195 dst_sel:DWORD dst_unused:UNUSED_PAD src0_sel:WORD_1 src1_sel:DWORD
	v_and_b32_sdwa v5, v0, v195 dst_sel:DWORD dst_unused:UNUSED_PAD src0_sel:WORD_1 src1_sel:DWORD
	v_and_b32_sdwa v2, v9, v195 dst_sel:DWORD dst_unused:UNUSED_PAD src0_sel:WORD_1 src1_sel:DWORD
	v_and_b32_sdwa v3, v8, v195 dst_sel:DWORD dst_unused:UNUSED_PAD src0_sel:WORD_1 src1_sel:DWORD
	v_add3_u32 v1, v1, v4, s39
	v_add3_u32 v0, v0, v5, s39
	v_add3_u32 v3, v8, v3, s39
	v_add3_u32 v2, v9, v2, s39
	v_and_b32_e32 v1, 0xffff0000, v1
	v_and_b32_e32 v0, 0xffff0000, v0
	v_or_b32_sdwa v1, v1, v2 dst_sel:DWORD dst_unused:UNUSED_PAD src0_sel:DWORD src1_sel:WORD_1
	v_or_b32_sdwa v0, v0, v3 dst_sel:DWORD dst_unused:UNUSED_PAD src0_sel:DWORD src1_sel:WORD_1
	flat_store_dwordx2 v[42:43], v[0:1] offset:3584
	v_lshl_add_u64 v[42:43], v[42:43], 0, s[50:51]
	s_cbranch_scc1 .LBB0_193

.LBB0_247:
	s_andn2_b64 vcc, exec, s[22:23]
	v_readlane_b32 s22, v255, 15
	v_readlane_b32 s24, v255, 28
	v_readlane_b32 s23, v255, 16
	v_readlane_b32 s25, v255, 29
	s_cbranch_vccnz .LBB0_252
	v_readlane_b32 s0, v255, 0
	v_readlane_b32 s1, v255, 1
	s_andn2_b64 vcc, exec, s[0:1]
	s_cbranch_vccnz .LBB0_252
	v_mbcnt_lo_u32_b32 v0, -1, 0
	v_mbcnt_hi_u32_b32 v0, -1, v0
	v_readlane_b32 s1, v255, 2
	v_add_u32_e32 v1, s65, v0
	v_readlane_b32 s12, v253, 0
	v_readfirstlane_b32 s0, v1
	s_ashr_i32 s0, s0, 6
	s_add_i32 s0, s0, s1
	v_readlane_b32 s13, v253, 1
	s_cmpk_gt_i32 s0, 0x1fff
	s_cbranch_scc1 .LBB0_252
	v_and_b32_e32 v0, 63, v0
	v_readlane_b32 s14, v255, 26
	v_lshlrev_b32_e32 v96, 4, v0
	v_readlane_b32 s15, v255, 27
	s_xor_b32 s26, s26, 0x2000000
	s_ashr_i32 s1, s0, 31
	v_lshl_add_u64 v[32:33], s[14:15], 0, v[96:97]
	s_mov_b64 s[14:15], 0x1000
	v_lshl_add_u64 v[34:35], v[32:33], 0, s[14:15]
	s_mov_b64 s[14:15], 0x1400
	v_lshl_add_u64 v[36:37], v[32:33], 0, s[14:15]
	s_mov_b64 s[14:15], 0x1800
	v_lshl_add_u64 v[38:39], v[32:33], 0, s[14:15]
	s_mov_b64 s[14:15], 0x1c00
	v_lshl_add_u64 v[40:41], v[32:33], 0, s[14:15]
	s_lshl_b64 s[14:15], s[0:1], 12
	s_lshl_b64 s[18:19], s[26:27], 1
	s_add_u32 s12, s12, s18
	s_addc_u32 s13, s13, s19
	v_lshlrev_b32_e32 v1, 2, v0
	s_add_u32 s12, s12, s14
	v_xor_b32_e32 v47, 4, v1
	v_xor_b32_e32 v50, 8, v1
	v_xor_b32_e32 v51, 16, v1
	v_xor_b32_e32 v52, 32, v1
	v_xor_b32_e32 v53, 64, v1
	v_xor_b32_e32 v54, 0x80, v1
	v_lshlrev_b32_e32 v0, 3, v0
	v_mov_b32_e32 v1, v97
	s_addc_u32 s13, s13, s15
	v_readlane_b32 s14, v255, 52
	v_lshl_add_u64 v[0:1], s[12:13], 0, v[0:1]
	s_mov_b64 s[12:13], 0xaa43000
	v_readlane_b32 s15, v255, 53
	v_lshl_add_u64 v[42:43], v[0:1], 0, s[12:13]
	s_lshl_b64 s[12:13], s[0:1], 13
	s_lshl_b64 s[14:15], s[14:15], 2
	v_readlane_b32 s1, v255, 17
	s_add_u32 s1, s1, s14
	v_readlane_b32 s14, v255, 22
	s_addc_u32 s14, s14, s15
	s_add_u32 s12, s1, s12
	s_addc_u32 s13, s14, s13
	v_lshl_add_u64 v[44:45], s[12:13], 0, v[96:97]
	v_readlane_b32 s12, v255, 50
	v_readlane_b32 s13, v255, 51
	global_load_dwordx4 v[64:67], v[32:33], off
	global_load_dwordx4 v[68:71], v[32:33], off offset:1024
	global_load_dwordx4 v[72:75], v[32:33], off offset:2048
	global_load_dwordx4 v[76:79], v[32:33], off offset:3072
	global_load_dwordx4 v[80:83], v[34:35], off
	global_load_dwordx4 v[84:87], v[36:37], off
	global_load_dwordx4 v[88:91], v[38:39], off
	global_load_dwordx4 v[92:95], v[40:41], off
	s_waitcnt vmcnt(0)
.LBB0_251:
	v_add_co_u32_e32 v0, vcc, 0xfffff000, v44
	s_add_i32 s0, s0, s12
	s_nop 0
	v_addc_co_u32_e32 v1, vcc, -1, v45, vcc
	global_load_dwordx4 v[28:31], v[0:1], off offset:-3072
	global_load_dwordx4 v[24:27], v[0:1], off offset:-2048
	global_load_dwordx4 v[20:23], v[0:1], off offset:-1024
	global_load_dwordx4 v[8:11], v[44:45], off offset:-4096
	global_load_dwordx4 v[12:15], v[44:45], off offset:-3072
	global_load_dwordx4 v[16:19], v[44:45], off offset:-2048
	s_cmpk_lt_i32 s0, 0x2000
	s_waitcnt vmcnt(0)
	v_mov_b32_e32 v4, v29
	v_mov_b32_e32 v5, v25
	v_mov_b32_e32 v2, v28
	v_mov_b32_e32 v3, v24
	v_pk_mul_f32 v[4:5], v[4:5], v[4:5]
	v_mov_b32_e32 v6, v31
	v_mov_b32_e32 v7, v27
	v_pk_fma_f32 v[2:3], v[2:3], v[2:3], v[4:5]
	v_mov_b32_e32 v4, v30
	v_mov_b32_e32 v5, v26
	v_pk_mul_f32 v[6:7], v[6:7], v[6:7]
	v_pk_mul_f32 v[0:1], v[22:23], v[22:23]
	v_pk_fma_f32 v[4:5], v[4:5], v[4:5], v[6:7]
	s_nop 0
	v_pk_add_f32 v[2:3], v[2:3], v[4:5]
	v_pk_mul_f32 v[4:5], v[20:21], v[20:21]
	v_pk_add_f32 v[2:3], v[2:3], v[2:3] op_sel:[0,1] op_sel_hi:[1,0]
	v_pk_mov_b32 v[6:7], v[4:5], v[0:1] op_sel:[1,0]
	v_mov_b32_e32 v5, v1
	v_pk_add_f32 v[0:1], v[6:7], v[4:5]
	v_mul_f32_e32 v4, v12, v12
	v_mul_f32_e32 v5, v13, v13
	v_pk_add_f32 v[0:1], v[0:1], v[0:1] op_sel:[0,1] op_sel_hi:[1,0]
	v_mov_b32_e32 v3, v4
	v_mov_b32_e32 v1, v5
	v_pk_add_f32 v[0:1], v[2:3], v[0:1]
	v_mul_f32_e32 v2, v9, v9
	v_mul_f32_e32 v4, v11, v11
	v_mul_f32_e32 v6, v14, v14
	v_mul_f32_e32 v7, v15, v15
	v_pk_fma_f32 v[2:3], v[8:9], v[8:9], v[2:3] op_sel_hi:[1,1,0]
	v_pk_fma_f32 v[4:5], v[10:11], v[10:11], v[4:5] op_sel_hi:[1,1,0]
	v_mov_b32_e32 v3, v6
	v_mov_b32_e32 v5, v7
	v_pk_add_f32 v[2:3], v[2:3], v[4:5]
	s_nop 0
	v_pk_add_f32 v[48:49], v[0:1], v[2:3]
	v_pk_mul_f32 v[0:1], v[18:19], v[18:19]
	v_pk_mul_f32 v[2:3], v[16:17], v[16:17]
	v_pk_add_f32 v[48:49], v[48:49], v[48:49] op_sel:[0,1] op_sel_hi:[1,0]
	v_pk_mov_b32 v[4:5], v[2:3], v[0:1] op_sel:[1,0]
	v_mov_b32_e32 v3, v1
	v_pk_add_f32 v[56:57], v[4:5], v[2:3]
	global_load_dwordx4 v[4:7], v[44:45], off offset:-1024
	global_load_dwordx4 v[0:3], v[44:45], off
	v_pk_add_f32 v[56:57], v[56:57], v[56:57] op_sel:[0,1] op_sel_hi:[1,0]
	v_lshl_add_u64 v[44:45], v[44:45], 0, s[24:25]
	s_waitcnt vmcnt(0)
	v_mul_f32_e32 v46, v0, v0
	v_mul_f32_e32 v55, v1, v1
	v_mov_b32_e32 v49, v46
	v_mov_b32_e32 v57, v55
	v_mul_f32_e32 v46, v5, v5
	v_mul_f32_e32 v58, v2, v2
	v_pk_add_f32 v[48:49], v[48:49], v[56:57]
	v_pk_fma_f32 v[56:57], v[4:5], v[4:5], v[46:47] op_sel_hi:[1,1,0]
	v_mul_f32_e32 v46, v7, v7
	v_mul_f32_e32 v60, v3, v3
	v_mov_b32_e32 v57, v58
	v_pk_fma_f32 v[58:59], v[6:7], v[6:7], v[46:47] op_sel_hi:[1,1,0]
	s_nop 0
	v_mov_b32_e32 v59, v60
	v_pk_add_f32 v[56:57], v[56:57], v[58:59]
	s_nop 0
	v_pk_add_f32 v[48:49], v[48:49], v[56:57]
	v_mov_b32_e32 v56, v64
	v_mov_b32_e32 v57, v65
	v_mov_b32_e32 v58, v66
	v_mov_b32_e32 v59, v67
	v_add_f32_e32 v46, v48, v49
	ds_bpermute_b32 v48, v47, v46
	v_mov_b32_e32 v49, v30
	v_mov_b32_e32 v30, v29
	s_waitcnt lgkmcnt(0)
	v_add_f32_e32 v46, v46, v48
	ds_bpermute_b32 v48, v50, v46
	s_waitcnt lgkmcnt(0)
	v_add_f32_e32 v46, v46, v48
	ds_bpermute_b32 v48, v51, v46
	s_waitcnt lgkmcnt(0)
	v_add_f32_e32 v46, v46, v48
	ds_bpermute_b32 v48, v52, v46
	s_waitcnt lgkmcnt(0)
	v_add_f32_e32 v46, v46, v48
	ds_bpermute_b32 v48, v53, v46
	s_waitcnt lgkmcnt(0)
	v_add_f32_e32 v46, v46, v48
	ds_bpermute_b32 v48, v54, v46
	s_waitcnt lgkmcnt(0)
	v_add_f32_e32 v46, v46, v48
	v_fmamk_f32 v46, v46, 0x3a000000, v194
	v_cmp_gt_f32_e32 vcc, s38, v46
	v_mul_f32_e32 v48, 0x4b800000, v46
	s_waitcnt vmcnt(0)
	v_mov_b32_e32 v60, v56
	v_cndmask_b32_e32 v46, v46, v48, vcc
	v_rsq_f32_e32 v46, v46
	v_mov_b32_e32 v61, v58
	v_mov_b32_e32 v58, v57
	v_mul_f32_e32 v48, 0x45800000, v46
	v_cndmask_b32_e32 v46, v46, v48, vcc
	v_mov_b32_e32 v48, v28
	v_pk_mul_f32 v[48:49], v[48:49], v[46:47] op_sel_hi:[1,0]
	v_pk_mul_f32 v[28:29], v[30:31], v[46:47] op_sel_hi:[1,0]
	v_pk_mul_f32 v[48:49], v[60:61], v[48:49]
	v_pk_mul_f32 v[28:29], v[58:59], v[28:29]
	v_and_b32_sdwa v30, v49, v195 dst_sel:DWORD dst_unused:UNUSED_PAD src0_sel:WORD_1 src1_sel:DWORD
	v_and_b32_sdwa v31, v48, v195 dst_sel:DWORD dst_unused:UNUSED_PAD src0_sel:WORD_1 src1_sel:DWORD
	v_add3_u32 v31, v48, v31, s39
	v_add3_u32 v30, v49, v30, s39
	v_and_b32_sdwa v48, v29, v195 dst_sel:DWORD dst_unused:UNUSED_PAD src0_sel:WORD_1 src1_sel:DWORD
	v_and_b32_sdwa v49, v28, v195 dst_sel:DWORD dst_unused:UNUSED_PAD src0_sel:WORD_1 src1_sel:DWORD
	v_add3_u32 v29, v29, v48, s39
	v_add3_u32 v28, v28, v49, s39
	v_and_b32_e32 v29, 0xffff0000, v29
	v_and_b32_e32 v28, 0xffff0000, v28
	v_or_b32_sdwa v29, v29, v30 dst_sel:DWORD dst_unused:UNUSED_PAD src0_sel:DWORD src1_sel:WORD_1
	v_or_b32_sdwa v28, v28, v31 dst_sel:DWORD dst_unused:UNUSED_PAD src0_sel:DWORD src1_sel:WORD_1
	flat_store_dwordx2 v[42:43], v[28:29]
	v_mov_b32_e32 v28, v68
	v_mov_b32_e32 v29, v69
	v_mov_b32_e32 v30, v70
	v_mov_b32_e32 v31, v71
	v_mov_b32_e32 v49, v26
	v_mov_b32_e32 v26, v25
	v_mov_b32_e32 v48, v24
	v_pk_mul_f32 v[24:25], v[26:27], v[46:47] op_sel_hi:[1,0]
	v_pk_mul_f32 v[48:49], v[48:49], v[46:47] op_sel_hi:[1,0]
	v_mov_b32_e32 v57, v30
	v_mov_b32_e32 v30, v29
	v_mov_b32_e32 v56, v28
	v_pk_mul_f32 v[24:25], v[30:31], v[24:25]
	v_pk_mul_f32 v[48:49], v[56:57], v[48:49]
	v_and_b32_sdwa v28, v25, v195 dst_sel:DWORD dst_unused:UNUSED_PAD src0_sel:WORD_1 src1_sel:DWORD
	v_and_b32_sdwa v29, v24, v195 dst_sel:DWORD dst_unused:UNUSED_PAD src0_sel:WORD_1 src1_sel:DWORD
	v_and_b32_sdwa v26, v49, v195 dst_sel:DWORD dst_unused:UNUSED_PAD src0_sel:WORD_1 src1_sel:DWORD
	v_and_b32_sdwa v27, v48, v195 dst_sel:DWORD dst_unused:UNUSED_PAD src0_sel:WORD_1 src1_sel:DWORD
	v_add3_u32 v25, v25, v28, s39
	v_add3_u32 v24, v24, v29, s39
	v_add3_u32 v27, v48, v27, s39
	v_add3_u32 v26, v49, v26, s39
	v_and_b32_e32 v25, 0xffff0000, v25
	v_and_b32_e32 v24, 0xffff0000, v24
	v_or_b32_sdwa v25, v25, v26 dst_sel:DWORD dst_unused:UNUSED_PAD src0_sel:DWORD src1_sel:WORD_1
	v_or_b32_sdwa v24, v24, v27 dst_sel:DWORD dst_unused:UNUSED_PAD src0_sel:DWORD src1_sel:WORD_1
	flat_store_dwordx2 v[42:43], v[24:25] offset:512
	v_mov_b32_e32 v24, v72
	v_mov_b32_e32 v25, v73
	v_mov_b32_e32 v26, v74
	v_mov_b32_e32 v27, v75
	v_mov_b32_e32 v29, v22
	v_mov_b32_e32 v22, v21
	v_mov_b32_e32 v28, v20
	v_pk_mul_f32 v[20:21], v[22:23], v[46:47] op_sel_hi:[1,0]
	v_pk_mul_f32 v[28:29], v[28:29], v[46:47] op_sel_hi:[1,0]
	v_mov_b32_e32 v31, v26
	v_mov_b32_e32 v26, v25
	v_mov_b32_e32 v30, v24
	v_pk_mul_f32 v[20:21], v[26:27], v[20:21]
	v_pk_mul_f32 v[28:29], v[30:31], v[28:29]
	v_and_b32_sdwa v24, v21, v195 dst_sel:DWORD dst_unused:UNUSED_PAD src0_sel:WORD_1 src1_sel:DWORD
	v_and_b32_sdwa v25, v20, v195 dst_sel:DWORD dst_unused:UNUSED_PAD src0_sel:WORD_1 src1_sel:DWORD
	v_and_b32_sdwa v22, v29, v195 dst_sel:DWORD dst_unused:UNUSED_PAD src0_sel:WORD_1 src1_sel:DWORD
	v_and_b32_sdwa v23, v28, v195 dst_sel:DWORD dst_unused:UNUSED_PAD src0_sel:WORD_1 src1_sel:DWORD
	v_add3_u32 v21, v21, v24, s39
	v_add3_u32 v20, v20, v25, s39
	v_add3_u32 v23, v28, v23, s39
	v_add3_u32 v22, v29, v22, s39
	v_and_b32_e32 v21, 0xffff0000, v21
	v_and_b32_e32 v20, 0xffff0000, v20
	v_or_b32_sdwa v21, v21, v22 dst_sel:DWORD dst_unused:UNUSED_PAD src0_sel:DWORD src1_sel:WORD_1
	v_or_b32_sdwa v20, v20, v23 dst_sel:DWORD dst_unused:UNUSED_PAD src0_sel:DWORD src1_sel:WORD_1
	flat_store_dwordx2 v[42:43], v[20:21] offset:1024
	v_mov_b32_e32 v20, v76
	v_mov_b32_e32 v21, v77
	v_mov_b32_e32 v22, v78
	v_mov_b32_e32 v23, v79
	v_mov_b32_e32 v25, v10
	v_mov_b32_e32 v10, v9
	v_mov_b32_e32 v24, v8
	v_pk_mul_f32 v[8:9], v[10:11], v[46:47] op_sel_hi:[1,0]
	v_pk_mul_f32 v[24:25], v[24:25], v[46:47] op_sel_hi:[1,0]
	v_mov_b32_e32 v27, v22
	v_mov_b32_e32 v22, v21
	v_mov_b32_e32 v26, v20
	v_pk_mul_f32 v[8:9], v[22:23], v[8:9]
	v_pk_mul_f32 v[24:25], v[26:27], v[24:25]
	v_and_b32_sdwa v20, v9, v195 dst_sel:DWORD dst_unused:UNUSED_PAD src0_sel:WORD_1 src1_sel:DWORD
	v_and_b32_sdwa v21, v8, v195 dst_sel:DWORD dst_unused:UNUSED_PAD src0_sel:WORD_1 src1_sel:DWORD
	v_and_b32_sdwa v10, v25, v195 dst_sel:DWORD dst_unused:UNUSED_PAD src0_sel:WORD_1 src1_sel:DWORD
	v_and_b32_sdwa v11, v24, v195 dst_sel:DWORD dst_unused:UNUSED_PAD src0_sel:WORD_1 src1_sel:DWORD
	v_add3_u32 v9, v9, v20, s39
	v_add3_u32 v8, v8, v21, s39
	v_add3_u32 v11, v24, v11, s39
	v_add3_u32 v10, v25, v10, s39
	v_and_b32_e32 v9, 0xffff0000, v9
	v_and_b32_e32 v8, 0xffff0000, v8
	v_or_b32_sdwa v9, v9, v10 dst_sel:DWORD dst_unused:UNUSED_PAD src0_sel:DWORD src1_sel:WORD_1
	v_or_b32_sdwa v8, v8, v11 dst_sel:DWORD dst_unused:UNUSED_PAD src0_sel:DWORD src1_sel:WORD_1
	flat_store_dwordx2 v[42:43], v[8:9] offset:1536
	v_mov_b32_e32 v8, v80
	v_mov_b32_e32 v9, v81
	v_mov_b32_e32 v10, v82
	v_mov_b32_e32 v11, v83
	v_mov_b32_e32 v21, v14
	v_mov_b32_e32 v14, v13
	v_mov_b32_e32 v20, v12
	v_pk_mul_f32 v[12:13], v[14:15], v[46:47] op_sel_hi:[1,0]
	v_pk_mul_f32 v[20:21], v[20:21], v[46:47] op_sel_hi:[1,0]
	v_mov_b32_e32 v23, v10
	v_mov_b32_e32 v10, v9
	v_mov_b32_e32 v22, v8
	v_pk_mul_f32 v[8:9], v[10:11], v[12:13]
	v_pk_mul_f32 v[20:21], v[22:23], v[20:21]
	v_and_b32_sdwa v12, v9, v195 dst_sel:DWORD dst_unused:UNUSED_PAD src0_sel:WORD_1 src1_sel:DWORD
	v_and_b32_sdwa v13, v8, v195 dst_sel:DWORD dst_unused:UNUSED_PAD src0_sel:WORD_1 src1_sel:DWORD
	v_and_b32_sdwa v10, v21, v195 dst_sel:DWORD dst_unused:UNUSED_PAD src0_sel:WORD_1 src1_sel:DWORD
	v_and_b32_sdwa v11, v20, v195 dst_sel:DWORD dst_unused:UNUSED_PAD src0_sel:WORD_1 src1_sel:DWORD
	v_add3_u32 v9, v9, v12, s39
	v_add3_u32 v8, v8, v13, s39
	v_add3_u32 v11, v20, v11, s39
	v_add3_u32 v10, v21, v10, s39
	v_and_b32_e32 v9, 0xffff0000, v9
	v_and_b32_e32 v8, 0xffff0000, v8
	v_or_b32_sdwa v9, v9, v10 dst_sel:DWORD dst_unused:UNUSED_PAD src0_sel:DWORD src1_sel:WORD_1
	v_or_b32_sdwa v8, v8, v11 dst_sel:DWORD dst_unused:UNUSED_PAD src0_sel:DWORD src1_sel:WORD_1
	flat_store_dwordx2 v[42:43], v[8:9] offset:2048
	v_mov_b32_e32 v8, v84
	v_mov_b32_e32 v9, v85
	v_mov_b32_e32 v10, v86
	v_mov_b32_e32 v11, v87
	v_mov_b32_e32 v12, v16
	v_mov_b32_e32 v13, v18
	v_pk_mul_f32 v[12:13], v[12:13], v[46:47] op_sel_hi:[1,0]
	v_mov_b32_e32 v18, v17
	v_mov_b32_e32 v14, v8
	v_mov_b32_e32 v15, v10
	v_pk_mul_f32 v[12:13], v[14:15], v[12:13]
	v_pk_mul_f32 v[14:15], v[18:19], v[46:47] op_sel_hi:[1,0]
	v_mov_b32_e32 v10, v9
	v_pk_mul_f32 v[8:9], v[10:11], v[14:15]
	v_and_b32_sdwa v10, v13, v195 dst_sel:DWORD dst_unused:UNUSED_PAD src0_sel:WORD_1 src1_sel:DWORD
	v_and_b32_sdwa v11, v12, v195 dst_sel:DWORD dst_unused:UNUSED_PAD src0_sel:WORD_1 src1_sel:DWORD
	v_add3_u32 v11, v12, v11, s39
	v_add3_u32 v10, v13, v10, s39
	v_and_b32_sdwa v12, v9, v195 dst_sel:DWORD dst_unused:UNUSED_PAD src0_sel:WORD_1 src1_sel:DWORD
	v_and_b32_sdwa v13, v8, v195 dst_sel:DWORD dst_unused:UNUSED_PAD src0_sel:WORD_1 src1_sel:DWORD
	v_add3_u32 v9, v9, v12, s39
	v_add3_u32 v8, v8, v13, s39
	v_and_b32_e32 v9, 0xffff0000, v9
	v_and_b32_e32 v8, 0xffff0000, v8
	v_or_b32_sdwa v9, v9, v10 dst_sel:DWORD dst_unused:UNUSED_PAD src0_sel:DWORD src1_sel:WORD_1
	v_or_b32_sdwa v8, v8, v11 dst_sel:DWORD dst_unused:UNUSED_PAD src0_sel:DWORD src1_sel:WORD_1
	flat_store_dwordx2 v[42:43], v[8:9] offset:2560
	v_mov_b32_e32 v8, v88
	v_mov_b32_e32 v9, v89
	v_mov_b32_e32 v10, v90
	v_mov_b32_e32 v11, v91
	v_mov_b32_e32 v13, v6
	v_mov_b32_e32 v6, v5
	v_mov_b32_e32 v12, v4
	v_pk_mul_f32 v[4:5], v[6:7], v[46:47] op_sel_hi:[1,0]
	v_pk_mul_f32 v[12:13], v[12:13], v[46:47] op_sel_hi:[1,0]
	v_mov_b32_e32 v15, v10
	v_mov_b32_e32 v10, v9
	v_mov_b32_e32 v14, v8
	v_pk_mul_f32 v[4:5], v[4:5], v[10:11]
	v_pk_mul_f32 v[12:13], v[12:13], v[14:15]
	v_and_b32_sdwa v8, v5, v195 dst_sel:DWORD dst_unused:UNUSED_PAD src0_sel:WORD_1 src1_sel:DWORD
	v_and_b32_sdwa v9, v4, v195 dst_sel:DWORD dst_unused:UNUSED_PAD src0_sel:WORD_1 src1_sel:DWORD
	v_and_b32_sdwa v6, v13, v195 dst_sel:DWORD dst_unused:UNUSED_PAD src0_sel:WORD_1 src1_sel:DWORD
	v_and_b32_sdwa v7, v12, v195 dst_sel:DWORD dst_unused:UNUSED_PAD src0_sel:WORD_1 src1_sel:DWORD
	v_add3_u32 v5, v5, v8, s39
	v_add3_u32 v4, v4, v9, s39
	v_add3_u32 v7, v12, v7, s39
	v_add3_u32 v6, v13, v6, s39
	v_and_b32_e32 v5, 0xffff0000, v5
	v_and_b32_e32 v4, 0xffff0000, v4
	v_or_b32_sdwa v5, v5, v6 dst_sel:DWORD dst_unused:UNUSED_PAD src0_sel:DWORD src1_sel:WORD_1
	v_or_b32_sdwa v4, v4, v7 dst_sel:DWORD dst_unused:UNUSED_PAD src0_sel:DWORD src1_sel:WORD_1
	flat_store_dwordx2 v[42:43], v[4:5] offset:3072
	v_mov_b32_e32 v4, v92
	v_mov_b32_e32 v5, v93
	v_mov_b32_e32 v6, v94
	v_mov_b32_e32 v7, v95
	v_mov_b32_e32 v9, v2
	v_mov_b32_e32 v2, v1
	v_mov_b32_e32 v8, v0
	v_pk_mul_f32 v[0:1], v[2:3], v[46:47] op_sel_hi:[1,0]
	v_pk_mul_f32 v[8:9], v[8:9], v[46:47] op_sel_hi:[1,0]
	v_mov_b32_e32 v11, v6
	v_mov_b32_e32 v6, v5
	v_mov_b32_e32 v10, v4
	v_pk_mul_f32 v[0:1], v[0:1], v[6:7]
	v_pk_mul_f32 v[8:9], v[8:9], v[10:11]
	v_and_b32_sdwa v4, v1, v195 dst_sel:DWORD dst_unused:UNUSED_PAD src0_sel:WORD_1 src1_sel:DWORD
	v_and_b32_sdwa v5, v0, v195 dst_sel:DWORD dst_unused:UNUSED_PAD src0_sel:WORD_1 src1_sel:DWORD
	v_and_b32_sdwa v2, v9, v195 dst_sel:DWORD dst_unused:UNUSED_PAD src0_sel:WORD_1 src1_sel:DWORD
	v_and_b32_sdwa v3, v8, v195 dst_sel:DWORD dst_unused:UNUSED_PAD src0_sel:WORD_1 src1_sel:DWORD
	v_add3_u32 v1, v1, v4, s39
	v_add3_u32 v0, v0, v5, s39
	v_add3_u32 v3, v8, v3, s39
	v_add3_u32 v2, v9, v2, s39
	v_and_b32_e32 v1, 0xffff0000, v1
	v_and_b32_e32 v0, 0xffff0000, v0
	v_or_b32_sdwa v1, v1, v2 dst_sel:DWORD dst_unused:UNUSED_PAD src0_sel:DWORD src1_sel:WORD_1
	v_or_b32_sdwa v0, v0, v3 dst_sel:DWORD dst_unused:UNUSED_PAD src0_sel:DWORD src1_sel:WORD_1
	flat_store_dwordx2 v[42:43], v[0:1] offset:3584
	v_lshl_add_u64 v[42:43], v[42:43], 0, s[22:23]
	s_cbranch_scc1 .LBB0_251
